# v51 + mLSTM state bf16 image written as packed dwords (DPP exchange between column pairs, 24 conflict-free ds_write_b32 instead of 48 ds_write_b16)
# speedup vs baseline: 1.0127x; 1.0053x over previous
; __device__ __forceinline__ bf16_t f2bf(float f) { const __bf16 r = (__bf16)f; bf16_t u; __builtin_memcpy(&u, &r, 2); return u; }
; __device__ __forceinline__ void mlstm_item(const P& p, const Ctx& c, int seg, int w, bool save) {
;     ...
; #pragma unroll
;         for (int j = 0; j < 12; ++j)
; #pragma unroll
;             for (int jj = 0; jj < 4; ++jj) Cimg[(e16 * 16 + quad * 4 + jj) * 392 + (2 * j + par) * 16 + l15] = f2bf(C[j][jj]);
.LBB0_369:
	v_lshlrev_b32_e32 v192, 2, v181
	v_add_u32_e32 v4, s79, v192
	v_lshlrev_b32_e32 v82, 1, v180
	v_mul_lo_u32 v4, v4, s33
	v_add3_u32 v4, s97, v82, v4
	v_and_b32_e32 v242, 1, v180
	v_cmp_ne_u32_e32 vcc, 0, v242
	v_mov_b32_e32 v243, 0x5040100
	v_mov_b32_e32 v244, 0x3020706
	v_mul_u32_u24_e32 v242, 0x61e, v242
	v_cndmask_b32_e32 v243, v243, v244, vcc
	v_add_u32_e32 v242, v4, v242
	s_waitcnt vmcnt(51)
	v_cvt_pk_bf16_f32 v234, v6, v8
	v_cvt_pk_bf16_f32 v235, v7, v9
	s_nop 0
	v_mov_b32_dpp v236, v234 quad_perm:[1,0,3,2] row_mask:0xf bank_mask:0xf bound_ctrl:1
	v_mov_b32_dpp v237, v235 quad_perm:[1,0,3,2] row_mask:0xf bank_mask:0xf bound_ctrl:1
	v_perm_b32 v238, v236, v234, v243
	v_perm_b32 v239, v237, v235, v243
	ds_write_b32 v242, v238
	ds_write_b32 v242, v239 offset:784
	s_waitcnt vmcnt(47)
	v_cvt_pk_bf16_f32 v234, v14, v16
	v_cvt_pk_bf16_f32 v235, v15, v17
	s_nop 0
	v_mov_b32_dpp v236, v234 quad_perm:[1,0,3,2] row_mask:0xf bank_mask:0xf bound_ctrl:1
	v_mov_b32_dpp v237, v235 quad_perm:[1,0,3,2] row_mask:0xf bank_mask:0xf bound_ctrl:1
	v_perm_b32 v238, v236, v234, v243
	v_perm_b32 v239, v237, v235, v243
	ds_write_b32 v242, v238 offset:64
	ds_write_b32 v242, v239 offset:848
	s_waitcnt vmcnt(43)
	v_cvt_pk_bf16_f32 v234, v22, v24
	v_cvt_pk_bf16_f32 v235, v23, v25
	s_nop 0
	v_mov_b32_dpp v236, v234 quad_perm:[1,0,3,2] row_mask:0xf bank_mask:0xf bound_ctrl:1
	v_mov_b32_dpp v237, v235 quad_perm:[1,0,3,2] row_mask:0xf bank_mask:0xf bound_ctrl:1
	v_perm_b32 v238, v236, v234, v243
	v_perm_b32 v239, v237, v235, v243
	ds_write_b32 v242, v238 offset:128
	ds_write_b32 v242, v239 offset:912
	s_waitcnt vmcnt(39)
	v_cvt_pk_bf16_f32 v234, v26, v28
	v_cvt_pk_bf16_f32 v235, v27, v29
	s_nop 0
	v_mov_b32_dpp v236, v234 quad_perm:[1,0,3,2] row_mask:0xf bank_mask:0xf bound_ctrl:1
	v_mov_b32_dpp v237, v235 quad_perm:[1,0,3,2] row_mask:0xf bank_mask:0xf bound_ctrl:1
	v_perm_b32 v238, v236, v234, v243
	v_perm_b32 v239, v237, v235, v243
	ds_write_b32 v242, v238 offset:192
	ds_write_b32 v242, v239 offset:976
	s_waitcnt vmcnt(35)
	v_cvt_pk_bf16_f32 v234, v10, v12
	v_cvt_pk_bf16_f32 v235, v11, v13
	s_nop 0
	v_mov_b32_dpp v236, v234 quad_perm:[1,0,3,2] row_mask:0xf bank_mask:0xf bound_ctrl:1
	v_mov_b32_dpp v237, v235 quad_perm:[1,0,3,2] row_mask:0xf bank_mask:0xf bound_ctrl:1
	v_perm_b32 v238, v236, v234, v243
	v_perm_b32 v239, v237, v235, v243
	ds_write_b32 v242, v238 offset:256
	ds_write_b32 v242, v239 offset:1040
	s_waitcnt vmcnt(31)
	v_cvt_pk_bf16_f32 v234, v18, v20
	v_cvt_pk_bf16_f32 v235, v19, v21
	s_nop 0
	v_mov_b32_dpp v236, v234 quad_perm:[1,0,3,2] row_mask:0xf bank_mask:0xf bound_ctrl:1
	v_mov_b32_dpp v237, v235 quad_perm:[1,0,3,2] row_mask:0xf bank_mask:0xf bound_ctrl:1
	v_perm_b32 v238, v236, v234, v243
	v_perm_b32 v239, v237, v235, v243
	ds_write_b32 v242, v238 offset:320
	ds_write_b32 v242, v239 offset:1104
	s_waitcnt vmcnt(27)
	v_cvt_pk_bf16_f32 v234, v30, v32
	v_cvt_pk_bf16_f32 v235, v31, v33
	s_nop 0
	v_mov_b32_dpp v236, v234 quad_perm:[1,0,3,2] row_mask:0xf bank_mask:0xf bound_ctrl:1
	v_mov_b32_dpp v237, v235 quad_perm:[1,0,3,2] row_mask:0xf bank_mask:0xf bound_ctrl:1
	v_perm_b32 v238, v236, v234, v243
	v_perm_b32 v239, v237, v235, v243
	ds_write_b32 v242, v238 offset:384
	ds_write_b32 v242, v239 offset:1168
	s_waitcnt vmcnt(23)
	v_cvt_pk_bf16_f32 v234, v34, v36
	v_cvt_pk_bf16_f32 v235, v35, v37
	s_nop 0
	v_mov_b32_dpp v236, v234 quad_perm:[1,0,3,2] row_mask:0xf bank_mask:0xf bound_ctrl:1
	v_mov_b32_dpp v237, v235 quad_perm:[1,0,3,2] row_mask:0xf bank_mask:0xf bound_ctrl:1
	v_perm_b32 v238, v236, v234, v243
	v_perm_b32 v239, v237, v235, v243
	ds_write_b32 v242, v238 offset:448
	ds_write_b32 v242, v239 offset:1232
	s_waitcnt vmcnt(19)
	v_cvt_pk_bf16_f32 v234, v38, v40
	v_cvt_pk_bf16_f32 v235, v39, v41
	s_nop 0
	v_mov_b32_dpp v236, v234 quad_perm:[1,0,3,2] row_mask:0xf bank_mask:0xf bound_ctrl:1
	v_mov_b32_dpp v237, v235 quad_perm:[1,0,3,2] row_mask:0xf bank_mask:0xf bound_ctrl:1
	v_perm_b32 v238, v236, v234, v243
	v_perm_b32 v239, v237, v235, v243
	ds_write_b32 v242, v238 offset:512
	ds_write_b32 v242, v239 offset:1296
	s_waitcnt vmcnt(15)
	v_cvt_pk_bf16_f32 v234, v42, v44
	v_cvt_pk_bf16_f32 v235, v43, v45
	s_nop 0
	v_mov_b32_dpp v236, v234 quad_perm:[1,0,3,2] row_mask:0xf bank_mask:0xf bound_ctrl:1
	v_mov_b32_dpp v237, v235 quad_perm:[1,0,3,2] row_mask:0xf bank_mask:0xf bound_ctrl:1
	v_perm_b32 v238, v236, v234, v243
	v_perm_b32 v239, v237, v235, v243
	ds_write_b32 v242, v238 offset:576
	ds_write_b32 v242, v239 offset:1360
	s_waitcnt vmcnt(11)
	v_cvt_pk_bf16_f32 v234, v46, v48
	v_cvt_pk_bf16_f32 v235, v47, v49
	s_nop 0
	v_mov_b32_dpp v236, v234 quad_perm:[1,0,3,2] row_mask:0xf bank_mask:0xf bound_ctrl:1
	v_mov_b32_dpp v237, v235 quad_perm:[1,0,3,2] row_mask:0xf bank_mask:0xf bound_ctrl:1
	v_perm_b32 v238, v236, v234, v243
	v_perm_b32 v239, v237, v235, v243
	ds_write_b32 v242, v238 offset:640
	ds_write_b32 v242, v239 offset:1424
	s_waitcnt vmcnt(7)
	v_cvt_pk_bf16_f32 v234, v54, v56
	v_cvt_pk_bf16_f32 v235, v55, v57
	s_nop 0
	v_mov_b32_dpp v236, v234 quad_perm:[1,0,3,2] row_mask:0xf bank_mask:0xf bound_ctrl:1
	v_mov_b32_dpp v237, v235 quad_perm:[1,0,3,2] row_mask:0xf bank_mask:0xf bound_ctrl:1
	v_perm_b32 v238, v236, v234, v243
	v_perm_b32 v239, v237, v235, v243
	ds_write_b32 v242, v238 offset:704
	ds_write_b32 v242, v239 offset:1488
	v_lshlrev_b32_e32 v4, 3, v191
	v_ashrrev_i32_e32 v82, 3, v191
	v_and_b32_e32 v4, 56, v4
	v_mul_lo_u32 v83, v82, s63
	v_lshlrev_b32_e32 v94, 1, v4
	v_add3_u32 v84, s28, v83, v94
	v_lshl_add_u32 v4, v4, 2, 0
	s_waitcnt lgkmcnt(0)
	s_barrier
; #define LAS __attribute__((address_space(3)))
; __device__ __forceinline__ unsigned pk2(float lo, float hi) { const bf2_t r = __builtin_convertvector((f32x2){lo, hi}, bf2_t); unsigned u; __builtin_memcpy(&u, &r, 4); return u; }
; __device__ __forceinline__ float bflo(unsigned u) { return __uint_as_float(u << 16); }
; __device__ __forceinline__ float bfhi(unsigned u) { return __uint_as_float(u & 0xFFFF0000u); }
; __device__ __forceinline__ void lds_barrier() { asm volatile("s_waitcnt lgkmcnt(0)" ::: "memory"); __builtin_amdgcn_s_barrier(); asm volatile("" ::: "memory"); }
; __device__ __forceinline__ void mlstm_item(const P& p, const Ctx& c, int seg, int w, bool save) {
;     ...
;     auto gl_chunk = [&](int ch, int tidv) { const int i = tidv >> 3, c8 = (tidv & 7) * 8;
;         pvt = *(const u32x4*)(VT + ((size_t)(b * 4 + h) * 384 + sl * 64 + i) * SEGT + ch * 64 + c8);
;         if (c.wv == 0) { plf = LOGF[(b * 4 + h) * SEGT + ch * 64 + c.lane]; pip = IPRE[(b * 4 + h) * SEGT + ch * 64 + c.lane]; } };
;     ...
;         lds_barrier();
;         { const int i = tidv >> 3, c8 = (tidv & 7) * 8;
;           const u32x4 raw = pvt;
;           *(LAS u32x4*)(VTs + i * 72 + c8) = raw;
;           const f32x4 w0 = *(const LAS f32x4*)(wgt + c8), w1 = *(const LAS f32x4*)(wgt + c8 + 4);
;           u32x4 sw; sw.x = pk2(bflo(raw.x) * w0[0], bfhi(raw.x) * w0[1]); sw.y = pk2(bflo(raw.y) * w0[2], bfhi(raw.y) * w0[3]);
;           sw.z = pk2(bflo(raw.z) * w1[0], bfhi(raw.z) * w1[1]); sw.w = pk2(bflo(raw.w) * w1[2], bfhi(raw.w) * w1[3]);
;           *(LAS u32x4*)(VWs + i * 72 + c8) = sw; }
;         if (ch + 1 < 8) gl_chunk(ch + 1, tidv);
	s_waitcnt vmcnt(6)
	ds_write_b128 v84, v[50:53]
	v_add_u32_e32 v4, 0x20200, v4
	ds_read_b128 v[84:87], v4
	ds_read_b128 v[88:91], v4 offset:16
	v_lshlrev_b32_e32 v92, 16, v50
	v_and_b32_e32 v93, 0xffff0000, v50
	s_cmpk_lg_i32 s84, 0x200
	s_waitcnt lgkmcnt(1)
	v_pk_mul_f32 v[84:85], v[84:85], v[92:93]
	v_lshlrev_b32_e32 v92, 16, v51
	v_and_b32_e32 v93, 0xffff0000, v51
	v_pk_mul_f32 v[86:87], v[86:87], v[92:93]
	v_cvt_pk_bf16_f32 v84, v84, v85
	v_cvt_pk_bf16_f32 v85, v86, v87
	v_lshlrev_b32_e32 v86, 16, v52
	v_and_b32_e32 v87, 0xffff0000, v52
	s_waitcnt lgkmcnt(0)
	v_pk_mul_f32 v[86:87], v[88:89], v[86:87]
	v_lshlrev_b32_e32 v88, 16, v53
	v_and_b32_e32 v89, 0xffff0000, v53
	v_pk_mul_f32 v[88:89], v[90:91], v[88:89]
	v_cvt_pk_bf16_f32 v86, v86, v87
	v_cvt_pk_bf16_f32 v87, v88, v89
	v_add3_u32 v4, s29, v83, v94
	s_cselect_b64 s[88:89], -1, 0
	s_cmpk_eq_i32 s84, 0x200
	s_mov_b64 s[90:91], 0x200
	ds_write_b128 v4, v[84:87]
	s_cbranch_scc1 .LBB0_373
	v_ashrrev_i32_e32 v83, 31, v82
	v_lshl_add_u64 v[50:51], s[70:71], 0, v[82:83]
	v_lshlrev_b64 v[50:51], 10, v[50:51]
	v_and_b32_e32 v4, 7, v191
	v_lshl_or_b32 v50, v4, 4, v50
	v_lshl_add_u64 v[50:51], s[82:83], 0, v[50:51]
	global_load_dwordx4 v[50:53], v[50:51], off
	s_and_b64 vcc, exec, s[16:17]
	s_cbranch_vccnz .LBB0_372
	v_add_u32_e32 v82, s84, v2
	v_ashrrev_i32_e32 v83, 31, v82
	v_lshlrev_b64 v[82:83], 2, v[82:83]
	v_lshl_add_u64 v[84:85], s[26:27], 0, v[82:83]
	v_lshl_add_u64 v[82:83], s[30:31], 0, v[82:83]
	global_load_dword v3, v[82:83], off
	global_load_dword v177, v[84:85], off
